# P8+P9 fused v3: per wave 64 tokens x 128 keys (sub-key fragments reused for 4 token tiles, 3 fragment sets in flight), LDS-transposed full-line score stores
# speedup vs baseline: 1.0330x; 1.0157x over previous
; DI unsigned pack2bf(float a, float b) { const f2_t v = {a, b}; return __builtin_bit_cast(unsigned, __builtin_convertvector(v, bf2_t)); }
; template <class Epi>
; DI void gemm_tile256(const u16* __restrict__ Ag, long lda, const u16* __restrict__ Bg, long ldb, int nk, char* shm, Epi&& epi) {
;     ...
;   __syncthreads();
; #pragma unroll
;   for (int m = 0; m < 8; ++m)
; #pragma unroll
;     for (int n = 0; n < 4; ++n) epi(wr * 128 + m * 16 + fr, wc * 64 + n * 16 + fq * 4, acc[m][n]);
; DI void phase8(const Params& P, char* smem) {
;     ...
;     gemm_tile256(h1b + (long)brow * 1024, 1024, WqT + (long)bcol * 1024, 1024, 32, smem, [&](int row, int col0, f32x4 v) {
;       *reinterpret_cast<uint2*>(Qp + (long)(brow + row) * 2048 + bcol + col0) = make_uint2(pack2bf(v[0], v[1]), pack2bf(v[2], v[3]));
;     });
.Lgemm_p8_kend:
	s_nop 7
	s_nop 3
	s_waitcnt vmcnt(0) lgkmcnt(0)
	s_barrier
	v_and_b32_e32 v186, 15, v208
	v_lshrrev_b32_e32 v187, 4, v208
	v_lshrrev_b32_e32 v206, 6, v189
	v_lshlrev_b32_e32 v206, 14, v206
	v_and_b32_e32 v207, 7, v186
	v_lshrrev_b32_e32 v224, 1, v187
	v_and_b32_e32 v225, 1, v187
	v_lshl_add_u32 v226, v186, 7, v206
	v_lshl_add_u32 v226, v225, 3, v226
	v_or_b32_e32 v227, 0, v224
	v_xor_b32_e32 v227, v227, v207
	v_lshl_add_u32 v232, v227, 4, v226
	v_or_b32_e32 v227, 2, v224
	v_xor_b32_e32 v227, v227, v207
	v_lshl_add_u32 v233, v227, 4, v226
	v_or_b32_e32 v227, 4, v224
	v_xor_b32_e32 v227, v227, v207
	v_lshl_add_u32 v234, v227, 4, v226
	v_or_b32_e32 v227, 6, v224
	v_xor_b32_e32 v227, v227, v207
	v_lshl_add_u32 v235, v227, 4, v226
	v_lshrrev_b32_e32 v228, 3, v208
	v_and_b32_e32 v229, 7, v208
	v_xor_b32_e32 v227, v229, v228
	v_lshl_add_u32 v236, v228, 7, v206
	v_lshl_add_u32 v236, v227, 4, v236
	v_lshl_add_u32 v227, v190, 7, v228
	v_add_u32_e32 v227, s10, v227
	v_lshlrev_b32_e32 v238, 12, v227
	v_bfe_u32 v227, v189, 6, 2
	v_lshl_add_u32 v238, v227, 7, v238
	v_lshl_add_u32 v238, v229, 4, v238
	v_mov_b32_e32 v239, 0
	s_and_b32 s26, s74, 7
	s_lshl_b32 s26, s26, 9
	s_add_u32 s26, s26, 0x8000000
	s_add_u32 s26, s78, s26
	s_addc_u32 s27, s79, 0
	v_lshl_add_u64 v[238:239], v[238:239], 0, s[26:27]
	s_mov_b32 s28, 0x8000
	s_mov_b32 s29, 0
	v_lshl_add_u64 v[240:241], v[238:239], 0, s[28:29]
	s_lshl_b32 s28, s28, 1
	v_cvt_pk_bf16_f32 v124, v124, v125
	v_cvt_pk_bf16_f32 v125, v126, v127
	ds_write_b64 v232, v[124:125] offset:0
	v_cvt_pk_bf16_f32 v120, v120, v121
	v_cvt_pk_bf16_f32 v121, v122, v123
	ds_write_b64 v233, v[120:121] offset:0
	v_cvt_pk_bf16_f32 v116, v116, v117
	v_cvt_pk_bf16_f32 v117, v118, v119
	ds_write_b64 v234, v[116:117] offset:0
	v_cvt_pk_bf16_f32 v112, v112, v113
	v_cvt_pk_bf16_f32 v113, v114, v115
	ds_write_b64 v235, v[112:113] offset:0
	v_cvt_pk_bf16_f32 v108, v108, v109
	v_cvt_pk_bf16_f32 v109, v110, v111
	ds_write_b64 v232, v[108:109] offset:2048
	v_cvt_pk_bf16_f32 v104, v104, v105
	v_cvt_pk_bf16_f32 v105, v106, v107
	ds_write_b64 v233, v[104:105] offset:2048
	v_cvt_pk_bf16_f32 v100, v100, v101
	v_cvt_pk_bf16_f32 v101, v102, v103
	ds_write_b64 v234, v[100:101] offset:2048
	v_cvt_pk_bf16_f32 v96, v96, v97
	v_cvt_pk_bf16_f32 v97, v98, v99
	ds_write_b64 v235, v[96:97] offset:2048
	v_cvt_pk_bf16_f32 v92, v92, v93
	v_cvt_pk_bf16_f32 v93, v94, v95
	ds_write_b64 v232, v[92:93] offset:4096
	v_cvt_pk_bf16_f32 v88, v88, v89
	v_cvt_pk_bf16_f32 v89, v90, v91
	ds_write_b64 v233, v[88:89] offset:4096
	v_cvt_pk_bf16_f32 v84, v84, v85
	v_cvt_pk_bf16_f32 v85, v86, v87
	ds_write_b64 v234, v[84:85] offset:4096
	v_cvt_pk_bf16_f32 v80, v80, v81
	v_cvt_pk_bf16_f32 v81, v82, v83
	ds_write_b64 v235, v[80:81] offset:4096
	v_cvt_pk_bf16_f32 v76, v76, v77
	v_cvt_pk_bf16_f32 v77, v78, v79
	ds_write_b64 v232, v[76:77] offset:6144
	v_cvt_pk_bf16_f32 v72, v72, v73
	v_cvt_pk_bf16_f32 v73, v74, v75
	ds_write_b64 v233, v[72:73] offset:6144
	v_cvt_pk_bf16_f32 v68, v68, v69
	v_cvt_pk_bf16_f32 v69, v70, v71
	ds_write_b64 v234, v[68:69] offset:6144
	v_cvt_pk_bf16_f32 v64, v64, v65
	v_cvt_pk_bf16_f32 v65, v66, v67
	ds_write_b64 v235, v[64:65] offset:6144
	v_cvt_pk_bf16_f32 v60, v60, v61
	v_cvt_pk_bf16_f32 v61, v62, v63
	ds_write_b64 v232, v[60:61] offset:8192
	v_cvt_pk_bf16_f32 v56, v56, v57
	v_cvt_pk_bf16_f32 v57, v58, v59
	ds_write_b64 v233, v[56:57] offset:8192
	v_cvt_pk_bf16_f32 v52, v52, v53
	v_cvt_pk_bf16_f32 v53, v54, v55
	ds_write_b64 v234, v[52:53] offset:8192
	v_cvt_pk_bf16_f32 v48, v48, v49
	v_cvt_pk_bf16_f32 v49, v50, v51
	ds_write_b64 v235, v[48:49] offset:8192
	v_cvt_pk_bf16_f32 v44, v44, v45
	v_cvt_pk_bf16_f32 v45, v46, v47
	ds_write_b64 v232, v[44:45] offset:10240
	v_cvt_pk_bf16_f32 v40, v40, v41
	v_cvt_pk_bf16_f32 v41, v42, v43
	ds_write_b64 v233, v[40:41] offset:10240
	v_cvt_pk_bf16_f32 v36, v36, v37
	v_cvt_pk_bf16_f32 v37, v38, v39
	ds_write_b64 v234, v[36:37] offset:10240
	v_cvt_pk_bf16_f32 v32, v32, v33
	v_cvt_pk_bf16_f32 v33, v34, v35
	ds_write_b64 v235, v[32:33] offset:10240
	v_cvt_pk_bf16_f32 v28, v28, v29
	v_cvt_pk_bf16_f32 v29, v30, v31
	ds_write_b64 v232, v[28:29] offset:12288
	v_cvt_pk_bf16_f32 v24, v24, v25
	v_cvt_pk_bf16_f32 v25, v26, v27
	ds_write_b64 v233, v[24:25] offset:12288
	v_cvt_pk_bf16_f32 v20, v20, v21
	v_cvt_pk_bf16_f32 v21, v22, v23
	ds_write_b64 v234, v[20:21] offset:12288
	v_cvt_pk_bf16_f32 v16, v16, v17
	v_cvt_pk_bf16_f32 v17, v18, v19
	ds_write_b64 v235, v[16:17] offset:12288
	v_cvt_pk_bf16_f32 v12, v12, v13
	v_cvt_pk_bf16_f32 v13, v14, v15
	ds_write_b64 v232, v[12:13] offset:14336
	v_cvt_pk_bf16_f32 v8, v8, v9
	v_cvt_pk_bf16_f32 v9, v10, v11
	ds_write_b64 v233, v[8:9] offset:14336
	v_cvt_pk_bf16_f32 v4, v4, v5
	v_cvt_pk_bf16_f32 v5, v6, v7
	ds_write_b64 v234, v[4:5] offset:14336
	v_cvt_pk_bf16_f32 v0, v0, v1
	v_cvt_pk_bf16_f32 v1, v2, v3
	ds_write_b64 v235, v[0:1] offset:14336
	s_waitcnt lgkmcnt(0)
	s_barrier
; #define TILE_LOOP(tile, N, C)                                                                                          \
;   for (int q0_ = (RBLK >> 3) * 2, tile = 0;                                                                            \
;        q0_ < (N) / 8 && ((tile = xcd_tile((q0_ + VHALF < (N) / 8 ? q0_ + VHALF : q0_), RBLK & 7, (C))), true);          \
;        q0_ += (RGRID >> 3) * 2)
; DI void phase9(const Params& P, char* smem) {
;     ...
;   TILE_LOOP(tile, 256 * 16, 16) {
;     const int brow = (tile >> 4) * 128, hc = tile & 15;
;     gemm_tile<false>(Qp + (long)brow * 2048 + hc * 128, 2048, SKb + (long)hc * 128 * 128, 128, 0, 2, 0, 0, smem, [&](int row0, int col, f32x4 v) {
;       typedef _Float16 h4 __attribute__((ext_vector_type(4)));
;       h4 hv; hv[0] = (_Float16)v[0]; hv[1] = (_Float16)v[1]; hv[2] = (_Float16)v[2]; hv[3] = (_Float16)v[3];
;       *reinterpret_cast<h4*>(ST + ((long)(hc * 128 + col)) * NTOK + brow + row0) = hv;
;     });
	v_lshrrev_b32_e32 v224, 6, v189
	v_lshrrev_b32_e32 v228, 1, v224
	v_and_b32_e32 v229, 1, v224
	v_lshrrev_b32_e32 v225, 1, v228
	v_and_b32_e32 v226, 1, v228
	v_lshlrev_b32_e32 v225, 16, v225
	v_lshl_add_u32 v225, v229, 15, v225
	v_lshl_add_u32 v226, v226, 6, v186
	v_lshl_add_u32 v225, v226, 7, v225
	v_and_b32_e32 v227, 7, v186
	v_xor_b32_e32 v227, v227, v187
	v_lshl_add_u32 v232, v227, 4, v225
	v_xor_b32_e32 v227, 4, v227
	v_lshl_add_u32 v233, v227, 4, v225
	ds_read_b128 v[0:3], v232 offset:0
	ds_read_b128 v[4:7], v233 offset:0
	ds_read_b128 v[8:11], v232 offset:16384
	ds_read_b128 v[12:15], v233 offset:16384
	ds_read_b128 v[16:19], v232 offset:2048
	ds_read_b128 v[20:23], v233 offset:2048
	ds_read_b128 v[24:27], v232 offset:18432
	ds_read_b128 v[28:31], v233 offset:18432
	ds_read_b128 v[32:35], v232 offset:4096
	ds_read_b128 v[36:39], v233 offset:4096
	ds_read_b128 v[40:43], v232 offset:20480
	ds_read_b128 v[44:47], v233 offset:20480
	ds_read_b128 v[48:51], v232 offset:6144
	ds_read_b128 v[52:55], v233 offset:6144
	ds_read_b128 v[56:59], v232 offset:22528
	ds_read_b128 v[60:63], v233 offset:22528
	s_and_b32 s26, s74, 7
	s_lshl_b32 s26, s26, 16
	s_add_u32 s26, s26, 0x18a80000
	s_add_u32 s26, s78, s26
	s_addc_u32 s27, s79, 0
	v_lshlrev_b32_e32 v234, 8, v186
	v_lshl_add_u32 v234, v187, 4, v234
	v_lshl_add_u32 v234, v229, 15, v234
	s_and_b32 s28, s74, 7
	s_cmp_lt_u32 s28, 4
	s_cselect_b32 s29, 0x6000000, 0
	s_sub_u32 s29, 0x10000000, s29
	s_lshl_b32 s28, s28, 24
	s_add_u32 s28, s28, s29
	s_add_u32 s28, s78, s28
	s_addc_u32 s29, s79, 0
	v_lshrrev_b32_e32 v226, 1, v187
	v_lshl_add_u32 v226, v228, 3, v226
	v_xor_b32_e32 v226, v226, v186
	v_and_b32_e32 v227, 1, v187
	v_lshlrev_b32_e32 v227, 3, v227
	v_lshl_add_u32 v227, v226, 4, v227
	v_lshl_add_u32 v227, v186, 9, v227
	v_lshl_add_u32 v236, v229, 16, v227
	v_xor_b32_e32 v237, 32, v236
	v_xor_b32_e32 v242, 64, v236
	v_xor_b32_e32 v243, 96, v236
	v_lshrrev_b32_e32 v226, 5, v208
	v_and_b32_e32 v227, 31, v208
	v_lshl_add_u32 v225, v224, 5, v226
	v_xor_b32_e32 v226, v227, v226
	v_lshlrev_b32_e32 v226, 4, v226
	v_lshl_add_u32 v240, v225, 9, v226
	s_lshl_b32 s10, s10, 1
	v_lshl_add_u32 v241, v227, 4, s10
	s_lshr_b32 s10, s10, 1
	v_lshl_add_u32 v241, v225, 16, v241
	v_add_u32_e32 v235, 0x0, v234
	global_load_dwordx4 v[64:67], v235, s[26:27] offset:0
	global_load_dwordx4 v[68:71], v235, s[26:27] offset:64
	global_load_dwordx4 v[72:75], v235, s[26:27] offset:128
	global_load_dwordx4 v[76:79], v235, s[26:27] offset:192
	v_add_u32_e32 v235, 0x1000, v234
	global_load_dwordx4 v[80:83], v235, s[26:27] offset:0
	global_load_dwordx4 v[84:87], v235, s[26:27] offset:64
	global_load_dwordx4 v[88:91], v235, s[26:27] offset:128
	global_load_dwordx4 v[92:95], v235, s[26:27] offset:192
	v_add_u32_e32 v235, 0x2000, v234
	global_load_dwordx4 v[112:115], v235, s[26:27] offset:0
	global_load_dwordx4 v[116:119], v235, s[26:27] offset:64
	global_load_dwordx4 v[120:123], v235, s[26:27] offset:128
	global_load_dwordx4 v[124:127], v235, s[26:27] offset:192
	s_waitcnt lgkmcnt(0)
	s_barrier
	s_waitcnt vmcnt(8)
	v_mfma_f32_16x16x32_bf16 v[96:99], v[0:3], v[64:67], 0
	v_mfma_f32_16x16x32_bf16 v[96:99], v[4:7], v[68:71], v[96:99]
	v_mfma_f32_16x16x32_bf16 v[96:99], v[8:11], v[72:75], v[96:99]
	v_mfma_f32_16x16x32_bf16 v[96:99], v[12:15], v[76:79], v[96:99]
	v_mfma_f32_16x16x32_bf16 v[100:103], v[16:19], v[64:67], 0
	v_mfma_f32_16x16x32_bf16 v[100:103], v[20:23], v[68:71], v[100:103]
	v_mfma_f32_16x16x32_bf16 v[100:103], v[24:27], v[72:75], v[100:103]
	v_mfma_f32_16x16x32_bf16 v[100:103], v[28:31], v[76:79], v[100:103]
	v_mfma_f32_16x16x32_bf16 v[104:107], v[32:35], v[64:67], 0
	v_mfma_f32_16x16x32_bf16 v[104:107], v[36:39], v[68:71], v[104:107]
	v_mfma_f32_16x16x32_bf16 v[104:107], v[40:43], v[72:75], v[104:107]
	v_mfma_f32_16x16x32_bf16 v[104:107], v[44:47], v[76:79], v[104:107]
	v_mfma_f32_16x16x32_bf16 v[108:111], v[48:51], v[64:67], 0
	v_mfma_f32_16x16x32_bf16 v[108:111], v[52:55], v[68:71], v[108:111]
	v_mfma_f32_16x16x32_bf16 v[108:111], v[56:59], v[72:75], v[108:111]
	v_mfma_f32_16x16x32_bf16 v[108:111], v[60:63], v[76:79], v[108:111]
	s_nop 7
	s_nop 3
	v_cvt_pk_f16_f32 v212, v96, v97
	v_cvt_pk_f16_f32 v213, v98, v99
	v_cvt_pk_f16_f32 v214, v100, v101
	v_cvt_pk_f16_f32 v215, v102, v103
	v_cvt_pk_f16_f32 v216, v104, v105
	v_cvt_pk_f16_f32 v217, v106, v107
	v_cvt_pk_f16_f32 v218, v108, v109
	v_cvt_pk_f16_f32 v219, v110, v111
	ds_write_b64 v236, v[212:213] offset:0
	ds_write_b64 v237, v[214:215] offset:0
	ds_write_b64 v242, v[216:217] offset:0
	ds_write_b64 v243, v[218:219] offset:0
	v_add_u32_e32 v235, 0x3000, v234
	global_load_dwordx4 v[64:67], v235, s[26:27] offset:0
	global_load_dwordx4 v[68:71], v235, s[26:27] offset:64
	global_load_dwordx4 v[72:75], v235, s[26:27] offset:128
	global_load_dwordx4 v[76:79], v235, s[26:27] offset:192
	s_waitcnt vmcnt(8)
; #define TILE_LOOP(tile, N, C)                                                                                          \
;   for (int q0_ = (RBLK >> 3) * 2, tile = 0;                                                                            \
;        q0_ < (N) / 8 && ((tile = xcd_tile((q0_ + VHALF < (N) / 8 ? q0_ + VHALF : q0_), RBLK & 7, (C))), true);          \
;        q0_ += (RGRID >> 3) * 2)
; DI void phase9(const Params& P, char* smem) {
;     ...
;   TILE_LOOP(tile, 256 * 16, 16) {
;     const int brow = (tile >> 4) * 128, hc = tile & 15;
;     gemm_tile<false>(Qp + (long)brow * 2048 + hc * 128, 2048, SKb + (long)hc * 128 * 128, 128, 0, 2, 0, 0, smem, [&](int row0, int col, f32x4 v) {
;       typedef _Float16 h4 __attribute__((ext_vector_type(4)));
;       h4 hv; hv[0] = (_Float16)v[0]; hv[1] = (_Float16)v[1]; hv[2] = (_Float16)v[2]; hv[3] = (_Float16)v[3];
;       *reinterpret_cast<h4*>(ST + ((long)(hc * 128 + col)) * NTOK + brow + row0) = hv;
;     });
	v_mfma_f32_16x16x32_bf16 v[96:99], v[0:3], v[80:83], 0
	v_mfma_f32_16x16x32_bf16 v[96:99], v[4:7], v[84:87], v[96:99]
	v_mfma_f32_16x16x32_bf16 v[96:99], v[8:11], v[88:91], v[96:99]
	v_mfma_f32_16x16x32_bf16 v[96:99], v[12:15], v[92:95], v[96:99]
	v_mfma_f32_16x16x32_bf16 v[100:103], v[16:19], v[80:83], 0
	v_mfma_f32_16x16x32_bf16 v[100:103], v[20:23], v[84:87], v[100:103]
	v_mfma_f32_16x16x32_bf16 v[100:103], v[24:27], v[88:91], v[100:103]
	v_mfma_f32_16x16x32_bf16 v[100:103], v[28:31], v[92:95], v[100:103]
	v_mfma_f32_16x16x32_bf16 v[104:107], v[32:35], v[80:83], 0
	v_mfma_f32_16x16x32_bf16 v[104:107], v[36:39], v[84:87], v[104:107]
	v_mfma_f32_16x16x32_bf16 v[104:107], v[40:43], v[88:91], v[104:107]
	v_mfma_f32_16x16x32_bf16 v[104:107], v[44:47], v[92:95], v[104:107]
	v_mfma_f32_16x16x32_bf16 v[108:111], v[48:51], v[80:83], 0
	v_mfma_f32_16x16x32_bf16 v[108:111], v[52:55], v[84:87], v[108:111]
	v_mfma_f32_16x16x32_bf16 v[108:111], v[56:59], v[88:91], v[108:111]
	v_mfma_f32_16x16x32_bf16 v[108:111], v[60:63], v[92:95], v[108:111]
	s_nop 7
	s_nop 3
	v_cvt_pk_f16_f32 v212, v96, v97
	v_cvt_pk_f16_f32 v213, v98, v99
	v_cvt_pk_f16_f32 v214, v100, v101
	v_cvt_pk_f16_f32 v215, v102, v103
	v_cvt_pk_f16_f32 v216, v104, v105
	v_cvt_pk_f16_f32 v217, v106, v107
	v_cvt_pk_f16_f32 v218, v108, v109
	v_cvt_pk_f16_f32 v219, v110, v111
	ds_write_b64 v236, v[212:213] offset:8192
	ds_write_b64 v237, v[214:215] offset:8192
	ds_write_b64 v242, v[216:217] offset:8192
	ds_write_b64 v243, v[218:219] offset:8192
	v_add_u32_e32 v235, 0x4000, v234
	global_load_dwordx4 v[80:83], v235, s[26:27] offset:0
	global_load_dwordx4 v[84:87], v235, s[26:27] offset:64
	global_load_dwordx4 v[88:91], v235, s[26:27] offset:128
	global_load_dwordx4 v[92:95], v235, s[26:27] offset:192
	s_waitcnt vmcnt(8)
	v_mfma_f32_16x16x32_bf16 v[96:99], v[0:3], v[112:115], 0
	v_mfma_f32_16x16x32_bf16 v[96:99], v[4:7], v[116:119], v[96:99]
	v_mfma_f32_16x16x32_bf16 v[96:99], v[8:11], v[120:123], v[96:99]
	v_mfma_f32_16x16x32_bf16 v[96:99], v[12:15], v[124:127], v[96:99]
	v_mfma_f32_16x16x32_bf16 v[100:103], v[16:19], v[112:115], 0
	v_mfma_f32_16x16x32_bf16 v[100:103], v[20:23], v[116:119], v[100:103]
	v_mfma_f32_16x16x32_bf16 v[100:103], v[24:27], v[120:123], v[100:103]
	v_mfma_f32_16x16x32_bf16 v[100:103], v[28:31], v[124:127], v[100:103]
	v_mfma_f32_16x16x32_bf16 v[104:107], v[32:35], v[112:115], 0
	v_mfma_f32_16x16x32_bf16 v[104:107], v[36:39], v[116:119], v[104:107]
	v_mfma_f32_16x16x32_bf16 v[104:107], v[40:43], v[120:123], v[104:107]
	v_mfma_f32_16x16x32_bf16 v[104:107], v[44:47], v[124:127], v[104:107]
	v_mfma_f32_16x16x32_bf16 v[108:111], v[48:51], v[112:115], 0
	v_mfma_f32_16x16x32_bf16 v[108:111], v[52:55], v[116:119], v[108:111]
	v_mfma_f32_16x16x32_bf16 v[108:111], v[56:59], v[120:123], v[108:111]
	v_mfma_f32_16x16x32_bf16 v[108:111], v[60:63], v[124:127], v[108:111]
	s_nop 7
	s_nop 3
	v_cvt_pk_f16_f32 v212, v96, v97
	v_cvt_pk_f16_f32 v213, v98, v99
	v_cvt_pk_f16_f32 v214, v100, v101
	v_cvt_pk_f16_f32 v215, v102, v103
	v_cvt_pk_f16_f32 v216, v104, v105
	v_cvt_pk_f16_f32 v217, v106, v107
	v_cvt_pk_f16_f32 v218, v108, v109
	v_cvt_pk_f16_f32 v219, v110, v111
	ds_write_b64 v236, v[212:213] offset:16384
	ds_write_b64 v237, v[214:215] offset:16384
	ds_write_b64 v242, v[216:217] offset:16384
	ds_write_b64 v243, v[218:219] offset:16384
	v_add_u32_e32 v235, 0x5000, v234
	global_load_dwordx4 v[112:115], v235, s[26:27] offset:0
	global_load_dwordx4 v[116:119], v235, s[26:27] offset:64
	global_load_dwordx4 v[120:123], v235, s[26:27] offset:128
	global_load_dwordx4 v[124:127], v235, s[26:27] offset:192
	s_waitcnt vmcnt(8)
	v_mfma_f32_16x16x32_bf16 v[96:99], v[0:3], v[64:67], 0
	v_mfma_f32_16x16x32_bf16 v[96:99], v[4:7], v[68:71], v[96:99]
	v_mfma_f32_16x16x32_bf16 v[96:99], v[8:11], v[72:75], v[96:99]
	v_mfma_f32_16x16x32_bf16 v[96:99], v[12:15], v[76:79], v[96:99]
	v_mfma_f32_16x16x32_bf16 v[100:103], v[16:19], v[64:67], 0
	v_mfma_f32_16x16x32_bf16 v[100:103], v[20:23], v[68:71], v[100:103]
	v_mfma_f32_16x16x32_bf16 v[100:103], v[24:27], v[72:75], v[100:103]
	v_mfma_f32_16x16x32_bf16 v[100:103], v[28:31], v[76:79], v[100:103]
	v_mfma_f32_16x16x32_bf16 v[104:107], v[32:35], v[64:67], 0
	v_mfma_f32_16x16x32_bf16 v[104:107], v[36:39], v[68:71], v[104:107]
	v_mfma_f32_16x16x32_bf16 v[104:107], v[40:43], v[72:75], v[104:107]
	v_mfma_f32_16x16x32_bf16 v[104:107], v[44:47], v[76:79], v[104:107]
	v_mfma_f32_16x16x32_bf16 v[108:111], v[48:51], v[64:67], 0
	v_mfma_f32_16x16x32_bf16 v[108:111], v[52:55], v[68:71], v[108:111]
	v_mfma_f32_16x16x32_bf16 v[108:111], v[56:59], v[72:75], v[108:111]
	v_mfma_f32_16x16x32_bf16 v[108:111], v[60:63], v[76:79], v[108:111]
	s_nop 7
	s_nop 3
	v_cvt_pk_f16_f32 v212, v96, v97
	v_cvt_pk_f16_f32 v213, v98, v99
	v_cvt_pk_f16_f32 v214, v100, v101
	v_cvt_pk_f16_f32 v215, v102, v103
	v_cvt_pk_f16_f32 v216, v104, v105
	v_cvt_pk_f16_f32 v217, v106, v107
	v_cvt_pk_f16_f32 v218, v108, v109
	v_cvt_pk_f16_f32 v219, v110, v111
	ds_write_b64 v236, v[212:213] offset:24576
	ds_write_b64 v237, v[214:215] offset:24576
	ds_write_b64 v242, v[216:217] offset:24576
	ds_write_b64 v243, v[218:219] offset:24576
	v_add_u32_e32 v235, 0x6000, v234
	global_load_dwordx4 v[64:67], v235, s[26:27] offset:0
	global_load_dwordx4 v[68:71], v235, s[26:27] offset:64
	global_load_dwordx4 v[72:75], v235, s[26:27] offset:128
	global_load_dwordx4 v[76:79], v235, s[26:27] offset:192
	s_waitcnt vmcnt(8)
; #define TILE_LOOP(tile, N, C)                                                                                          \
;   for (int q0_ = (RBLK >> 3) * 2, tile = 0;                                                                            \
;        q0_ < (N) / 8 && ((tile = xcd_tile((q0_ + VHALF < (N) / 8 ? q0_ + VHALF : q0_), RBLK & 7, (C))), true);          \
;        q0_ += (RGRID >> 3) * 2)
; DI void phase9(const Params& P, char* smem) {
;     ...
;   TILE_LOOP(tile, 256 * 16, 16) {
;     const int brow = (tile >> 4) * 128, hc = tile & 15;
;     gemm_tile<false>(Qp + (long)brow * 2048 + hc * 128, 2048, SKb + (long)hc * 128 * 128, 128, 0, 2, 0, 0, smem, [&](int row0, int col, f32x4 v) {
;       typedef _Float16 h4 __attribute__((ext_vector_type(4)));
;       h4 hv; hv[0] = (_Float16)v[0]; hv[1] = (_Float16)v[1]; hv[2] = (_Float16)v[2]; hv[3] = (_Float16)v[3];
;       *reinterpret_cast<h4*>(ST + ((long)(hc * 128 + col)) * NTOK + brow + row0) = hv;
;     });
	v_mfma_f32_16x16x32_bf16 v[96:99], v[0:3], v[80:83], 0
	v_mfma_f32_16x16x32_bf16 v[96:99], v[4:7], v[84:87], v[96:99]
	v_mfma_f32_16x16x32_bf16 v[96:99], v[8:11], v[88:91], v[96:99]
	v_mfma_f32_16x16x32_bf16 v[96:99], v[12:15], v[92:95], v[96:99]
	v_mfma_f32_16x16x32_bf16 v[100:103], v[16:19], v[80:83], 0
	v_mfma_f32_16x16x32_bf16 v[100:103], v[20:23], v[84:87], v[100:103]
	v_mfma_f32_16x16x32_bf16 v[100:103], v[24:27], v[88:91], v[100:103]
	v_mfma_f32_16x16x32_bf16 v[100:103], v[28:31], v[92:95], v[100:103]
	v_mfma_f32_16x16x32_bf16 v[104:107], v[32:35], v[80:83], 0
	v_mfma_f32_16x16x32_bf16 v[104:107], v[36:39], v[84:87], v[104:107]
	v_mfma_f32_16x16x32_bf16 v[104:107], v[40:43], v[88:91], v[104:107]
	v_mfma_f32_16x16x32_bf16 v[104:107], v[44:47], v[92:95], v[104:107]
	v_mfma_f32_16x16x32_bf16 v[108:111], v[48:51], v[80:83], 0
	v_mfma_f32_16x16x32_bf16 v[108:111], v[52:55], v[84:87], v[108:111]
	v_mfma_f32_16x16x32_bf16 v[108:111], v[56:59], v[88:91], v[108:111]
	v_mfma_f32_16x16x32_bf16 v[108:111], v[60:63], v[92:95], v[108:111]
	s_nop 7
	s_nop 3
	v_cvt_pk_f16_f32 v212, v96, v97
	v_cvt_pk_f16_f32 v213, v98, v99
	v_cvt_pk_f16_f32 v214, v100, v101
	v_cvt_pk_f16_f32 v215, v102, v103
	v_cvt_pk_f16_f32 v216, v104, v105
	v_cvt_pk_f16_f32 v217, v106, v107
	v_cvt_pk_f16_f32 v218, v108, v109
	v_cvt_pk_f16_f32 v219, v110, v111
	ds_write_b64 v236, v[212:213] offset:32768
	ds_write_b64 v237, v[214:215] offset:32768
	ds_write_b64 v242, v[216:217] offset:32768
	ds_write_b64 v243, v[218:219] offset:32768
	v_add_u32_e32 v235, 0x7000, v234
	global_load_dwordx4 v[80:83], v235, s[26:27] offset:0
	global_load_dwordx4 v[84:87], v235, s[26:27] offset:64
	global_load_dwordx4 v[88:91], v235, s[26:27] offset:128
	global_load_dwordx4 v[92:95], v235, s[26:27] offset:192
	s_waitcnt vmcnt(8)
	v_mfma_f32_16x16x32_bf16 v[96:99], v[0:3], v[112:115], 0
	v_mfma_f32_16x16x32_bf16 v[96:99], v[4:7], v[116:119], v[96:99]
	v_mfma_f32_16x16x32_bf16 v[96:99], v[8:11], v[120:123], v[96:99]
	v_mfma_f32_16x16x32_bf16 v[96:99], v[12:15], v[124:127], v[96:99]
	v_mfma_f32_16x16x32_bf16 v[100:103], v[16:19], v[112:115], 0
	v_mfma_f32_16x16x32_bf16 v[100:103], v[20:23], v[116:119], v[100:103]
	v_mfma_f32_16x16x32_bf16 v[100:103], v[24:27], v[120:123], v[100:103]
	v_mfma_f32_16x16x32_bf16 v[100:103], v[28:31], v[124:127], v[100:103]
	v_mfma_f32_16x16x32_bf16 v[104:107], v[32:35], v[112:115], 0
	v_mfma_f32_16x16x32_bf16 v[104:107], v[36:39], v[116:119], v[104:107]
	v_mfma_f32_16x16x32_bf16 v[104:107], v[40:43], v[120:123], v[104:107]
	v_mfma_f32_16x16x32_bf16 v[104:107], v[44:47], v[124:127], v[104:107]
	v_mfma_f32_16x16x32_bf16 v[108:111], v[48:51], v[112:115], 0
	v_mfma_f32_16x16x32_bf16 v[108:111], v[52:55], v[116:119], v[108:111]
	v_mfma_f32_16x16x32_bf16 v[108:111], v[56:59], v[120:123], v[108:111]
	v_mfma_f32_16x16x32_bf16 v[108:111], v[60:63], v[124:127], v[108:111]
	s_nop 7
	s_nop 3
	v_cvt_pk_f16_f32 v212, v96, v97
	v_cvt_pk_f16_f32 v213, v98, v99
	v_cvt_pk_f16_f32 v214, v100, v101
	v_cvt_pk_f16_f32 v215, v102, v103
	v_cvt_pk_f16_f32 v216, v104, v105
	v_cvt_pk_f16_f32 v217, v106, v107
	v_cvt_pk_f16_f32 v218, v108, v109
	v_cvt_pk_f16_f32 v219, v110, v111
	ds_write_b64 v236, v[212:213] offset:40960
	ds_write_b64 v237, v[214:215] offset:40960
	ds_write_b64 v242, v[216:217] offset:40960
	ds_write_b64 v243, v[218:219] offset:40960
	s_waitcnt vmcnt(4)
	v_mfma_f32_16x16x32_bf16 v[96:99], v[0:3], v[64:67], 0
	v_mfma_f32_16x16x32_bf16 v[96:99], v[4:7], v[68:71], v[96:99]
	v_mfma_f32_16x16x32_bf16 v[96:99], v[8:11], v[72:75], v[96:99]
	v_mfma_f32_16x16x32_bf16 v[96:99], v[12:15], v[76:79], v[96:99]
	v_mfma_f32_16x16x32_bf16 v[100:103], v[16:19], v[64:67], 0
	v_mfma_f32_16x16x32_bf16 v[100:103], v[20:23], v[68:71], v[100:103]
	v_mfma_f32_16x16x32_bf16 v[100:103], v[24:27], v[72:75], v[100:103]
	v_mfma_f32_16x16x32_bf16 v[100:103], v[28:31], v[76:79], v[100:103]
	v_mfma_f32_16x16x32_bf16 v[104:107], v[32:35], v[64:67], 0
	v_mfma_f32_16x16x32_bf16 v[104:107], v[36:39], v[68:71], v[104:107]
	v_mfma_f32_16x16x32_bf16 v[104:107], v[40:43], v[72:75], v[104:107]
	v_mfma_f32_16x16x32_bf16 v[104:107], v[44:47], v[76:79], v[104:107]
	v_mfma_f32_16x16x32_bf16 v[108:111], v[48:51], v[64:67], 0
	v_mfma_f32_16x16x32_bf16 v[108:111], v[52:55], v[68:71], v[108:111]
	v_mfma_f32_16x16x32_bf16 v[108:111], v[56:59], v[72:75], v[108:111]
	v_mfma_f32_16x16x32_bf16 v[108:111], v[60:63], v[76:79], v[108:111]
	s_nop 7
	s_nop 3
	v_cvt_pk_f16_f32 v212, v96, v97
	v_cvt_pk_f16_f32 v213, v98, v99
	v_cvt_pk_f16_f32 v214, v100, v101
	v_cvt_pk_f16_f32 v215, v102, v103
	v_cvt_pk_f16_f32 v216, v104, v105
	v_cvt_pk_f16_f32 v217, v106, v107
	v_cvt_pk_f16_f32 v218, v108, v109
	v_cvt_pk_f16_f32 v219, v110, v111
	ds_write_b64 v236, v[212:213] offset:49152
	ds_write_b64 v237, v[214:215] offset:49152
	ds_write_b64 v242, v[216:217] offset:49152
	ds_write_b64 v243, v[218:219] offset:49152
	s_waitcnt vmcnt(0)
	v_mfma_f32_16x16x32_bf16 v[96:99], v[0:3], v[80:83], 0
	v_mfma_f32_16x16x32_bf16 v[96:99], v[4:7], v[84:87], v[96:99]
	v_mfma_f32_16x16x32_bf16 v[96:99], v[8:11], v[88:91], v[96:99]
	v_mfma_f32_16x16x32_bf16 v[96:99], v[12:15], v[92:95], v[96:99]
	v_mfma_f32_16x16x32_bf16 v[100:103], v[16:19], v[80:83], 0
	v_mfma_f32_16x16x32_bf16 v[100:103], v[20:23], v[84:87], v[100:103]
	v_mfma_f32_16x16x32_bf16 v[100:103], v[24:27], v[88:91], v[100:103]
	v_mfma_f32_16x16x32_bf16 v[100:103], v[28:31], v[92:95], v[100:103]
	v_mfma_f32_16x16x32_bf16 v[104:107], v[32:35], v[80:83], 0
	v_mfma_f32_16x16x32_bf16 v[104:107], v[36:39], v[84:87], v[104:107]
	v_mfma_f32_16x16x32_bf16 v[104:107], v[40:43], v[88:91], v[104:107]
	v_mfma_f32_16x16x32_bf16 v[104:107], v[44:47], v[92:95], v[104:107]
	v_mfma_f32_16x16x32_bf16 v[108:111], v[48:51], v[80:83], 0
	v_mfma_f32_16x16x32_bf16 v[108:111], v[52:55], v[84:87], v[108:111]
	v_mfma_f32_16x16x32_bf16 v[108:111], v[56:59], v[88:91], v[108:111]
	v_mfma_f32_16x16x32_bf16 v[108:111], v[60:63], v[92:95], v[108:111]
	s_nop 7
	s_nop 3
	v_cvt_pk_f16_f32 v212, v96, v97
	v_cvt_pk_f16_f32 v213, v98, v99
	v_cvt_pk_f16_f32 v214, v100, v101
	v_cvt_pk_f16_f32 v215, v102, v103
	v_cvt_pk_f16_f32 v216, v104, v105
	v_cvt_pk_f16_f32 v217, v106, v107
	v_cvt_pk_f16_f32 v218, v108, v109
	v_cvt_pk_f16_f32 v219, v110, v111
	ds_write_b64 v236, v[212:213] offset:57344
	ds_write_b64 v237, v[214:215] offset:57344
	ds_write_b64 v242, v[216:217] offset:57344
	ds_write_b64 v243, v[218:219] offset:57344
	s_waitcnt lgkmcnt(0)
	s_barrier
; DI void phase9(const Params& P, char* smem) {
;     ...
;     gemm_tile<false>(Qp + (long)brow * 2048 + hc * 128, 2048, SKb + (long)hc * 128 * 128, 128, 0, 2, 0, 0, smem, [&](int row0, int col, f32x4 v) {
;       typedef _Float16 h4 __attribute__((ext_vector_type(4)));
;       h4 hv; hv[0] = (_Float16)v[0]; hv[1] = (_Float16)v[1]; hv[2] = (_Float16)v[2]; hv[3] = (_Float16)v[3];
;       *reinterpret_cast<h4*>(ST + ((long)(hc * 128 + col)) * NTOK + brow + row0) = hv;
;     });
	v_xor_b32_e32 v238, 0x0, v240
	ds_read_b128 v[64:67], v238 offset:0
	v_xor_b32_e32 v238, 0x20, v240
	ds_read_b128 v[68:71], v238 offset:1024
	v_xor_b32_e32 v238, 0x40, v240
	ds_read_b128 v[72:75], v238 offset:2048
	v_xor_b32_e32 v238, 0x60, v240
	ds_read_b128 v[76:79], v238 offset:3072
	v_xor_b32_e32 v238, 0x80, v240
	ds_read_b128 v[80:83], v238 offset:4096
	v_xor_b32_e32 v238, 0xa0, v240
	ds_read_b128 v[84:87], v238 offset:5120
	v_xor_b32_e32 v238, 0xc0, v240
	ds_read_b128 v[88:91], v238 offset:6144
	v_xor_b32_e32 v238, 0xe0, v240
	ds_read_b128 v[92:95], v238 offset:7168
	s_waitcnt lgkmcnt(7)
	v_add_u32_e32 v239, 0x0, v241
	global_store_dwordx4 v239, v[64:67], s[28:29]
	s_waitcnt lgkmcnt(6)
	v_add_u32_e32 v239, 0x20000, v241
	global_store_dwordx4 v239, v[68:71], s[28:29]
	s_waitcnt lgkmcnt(5)
	v_add_u32_e32 v239, 0x40000, v241
	global_store_dwordx4 v239, v[72:75], s[28:29]
	s_waitcnt lgkmcnt(4)
	v_add_u32_e32 v239, 0x60000, v241
	global_store_dwordx4 v239, v[76:79], s[28:29]
	s_waitcnt lgkmcnt(3)
	v_add_u32_e32 v239, 0x80000, v241
	global_store_dwordx4 v239, v[80:83], s[28:29]
	s_waitcnt lgkmcnt(2)
	v_add_u32_e32 v239, 0xa0000, v241
	global_store_dwordx4 v239, v[84:87], s[28:29]
	s_waitcnt lgkmcnt(1)
	v_add_u32_e32 v239, 0xc0000, v241
	global_store_dwordx4 v239, v[88:91], s[28:29]
	s_waitcnt lgkmcnt(0)
	v_add_u32_e32 v239, 0xe0000, v241
	global_store_dwordx4 v239, v[92:95], s[28:29]
	v_xor_b32_e32 v238, 0x0, v240
	ds_read_b128 v[64:67], v238 offset:8192
	v_xor_b32_e32 v238, 0x20, v240
	ds_read_b128 v[68:71], v238 offset:9216
	v_xor_b32_e32 v238, 0x40, v240
	ds_read_b128 v[72:75], v238 offset:10240
	v_xor_b32_e32 v238, 0x60, v240
	ds_read_b128 v[76:79], v238 offset:11264
	v_xor_b32_e32 v238, 0x80, v240
	ds_read_b128 v[80:83], v238 offset:12288
	v_xor_b32_e32 v238, 0xa0, v240
	ds_read_b128 v[84:87], v238 offset:13312
	v_xor_b32_e32 v238, 0xc0, v240
	ds_read_b128 v[88:91], v238 offset:14336
	v_xor_b32_e32 v238, 0xe0, v240
	ds_read_b128 v[92:95], v238 offset:15360
	s_waitcnt lgkmcnt(7)
	v_add_u32_e32 v239, 0x100000, v241
	global_store_dwordx4 v239, v[64:67], s[28:29]
	s_waitcnt lgkmcnt(6)
	v_add_u32_e32 v239, 0x120000, v241
	global_store_dwordx4 v239, v[68:71], s[28:29]
	s_waitcnt lgkmcnt(5)
	v_add_u32_e32 v239, 0x140000, v241
	global_store_dwordx4 v239, v[72:75], s[28:29]
	s_waitcnt lgkmcnt(4)
	v_add_u32_e32 v239, 0x160000, v241
	global_store_dwordx4 v239, v[76:79], s[28:29]
	s_waitcnt lgkmcnt(3)
	v_add_u32_e32 v239, 0x180000, v241
	global_store_dwordx4 v239, v[80:83], s[28:29]
	s_waitcnt lgkmcnt(2)
	v_add_u32_e32 v239, 0x1a0000, v241
	global_store_dwordx4 v239, v[84:87], s[28:29]
	s_waitcnt lgkmcnt(1)
	v_add_u32_e32 v239, 0x1c0000, v241
	global_store_dwordx4 v239, v[88:91], s[28:29]
	s_waitcnt lgkmcnt(0)
	v_add_u32_e32 v239, 0x1e0000, v241
	global_store_dwordx4 v239, v[92:95], s[28:29]
	s_barrier
	s_add_i32 s75, s75, s5
	s_add_i32 s6, s6, s8
	s_cmpk_lt_i32 s75, 0x80
	s_cbranch_scc1 .LBB0_1068
